# baseline (speedup 1.0000x reference)
;     __device__ __forceinline__ void fused(f32x4 (&acc)[2][2][4][2], const Unit& u, int wr, int wc, int fr, int fq, LAS unsigned char* lds) const {
;     ...
;             for (int m = 0; m < 4; ++m) { const int rl = rl0 + ai * HALF + m * 16; const size_t roff = (size_t)(u.pm * BM + rl) * LDX + col0; float s = 0.f, q = 0.f;
; #pragma unroll
;                 for (int bj = 0; bj < 2; ++bj)
; #pragma unroll
;                     for (int n = 0; n < 2; ++n) { const u32x2 w = *(const u32x2*)(res + roff + bj * HALF + n * 16); f32x4 o = acc[ai][bj][m][n];
;                         o[0] += ALPHA * __uint_as_float(w.x << 16); o[1] += ALPHA * __uint_as_float(w.x & 0xffff0000u); o[2] += ALPHA * __uint_as_float(w.y << 16); o[3] += ALPHA * __uint_as_float(w.y & 0xffff0000u);
;                         acc[ai][bj][m][n] = o; s += (o[0] + o[1]) + (o[2] + o[3]); q += (o[0] * o[0] + o[1] * o[1]) + (o[2] * o[2] + o[3] * o[3]); }
;                 s += __shfl_xor(s, 16); s += __shfl_xor(s, 32); q += __shfl_xor(q, 16); q += __shfl_xor(q, 32);
;                 if (fq == 0) { P[(rl * 4 + wc) * 2] = s; P[(rl * 4 + wc) * 2 + 1] = q; }
.LBB0_551:
	s_lshl_b32 s2, s88, 8
	v_add_u32_e32 v138, s2, v219
	v_mov_b64_e32 v[136:137], s[28:29]
	v_ashrrev_i32_e32 v135, 31, v134
	v_mad_i64_i32 v[136:137], s[0:1], v138, s93, v[136:137]
	v_mov_b32_e32 v246, v200
	v_lshl_add_u64 v[140:141], v[134:135], 1, v[136:137]
	v_lshl_add_u64 v[198:199], v[134:135], 1, s[28:29]
	v_add_u32_e32 v188, s2, v219
	v_mad_i64_i32 v[188:189], s[0:1], v188, s93, v[198:199]
	global_load_dwordx2 v[188:189], v[188:189], off
	v_add_u32_e32 v190, s2, v219
	v_mad_i64_i32 v[190:191], s[0:1], v190, s93, v[198:199]
	global_load_dwordx2 v[190:191], v[190:191], off offset:32
	v_add_u32_e32 v192, s2, v219
	v_mad_i64_i32 v[192:193], s[0:1], v192, s93, v[198:199]
	global_load_dwordx2 v[192:193], v[192:193], off offset:256
	v_add_u32_e32 v194, s2, v219
	v_mad_i64_i32 v[194:195], s[0:1], v194, s93, v[198:199]
	global_load_dwordx2 v[194:195], v[194:195], off offset:288
	v_add_u32_e32 v196, s2, v221
	v_mad_i64_i32 v[196:197], s[0:1], v196, s93, v[198:199]
	global_load_dwordx2 v[196:197], v[196:197], off
	v_add_u32_e32 v208, s2, v221
	v_mad_i64_i32 v[208:209], s[0:1], v208, s93, v[198:199]
	global_load_dwordx2 v[208:209], v[208:209], off offset:32
	v_add_u32_e32 v210, s2, v221
	v_mad_i64_i32 v[210:211], s[0:1], v210, s93, v[198:199]
	global_load_dwordx2 v[210:211], v[210:211], off offset:256
	v_add_u32_e32 v212, s2, v221
	v_mad_i64_i32 v[212:213], s[0:1], v212, s93, v[198:199]
	global_load_dwordx2 v[212:213], v[212:213], off offset:288
	v_cmp_lt_i32_e32 vcc, v206, v204
	s_waitcnt vmcnt(7)
	v_mov_b32_e32 v136, v188
	v_mov_b32_e32 v137, v189
	v_add_u32_e32 v188, s2, v222
	v_mad_i64_i32 v[188:189], s[0:1], v188, s93, v[198:199]
	global_load_dwordx2 v[188:189], v[188:189], off
	v_lshlrev_b32_e32 v156, 16, v136
	v_and_b32_e32 v158, 0xffff0000, v136
	v_lshlrev_b32_e32 v154, 16, v137
	v_and_b32_e32 v152, 0xffff0000, v137
	v_cndmask_b32_e32 v64, v203, v206, vcc
	v_lshlrev_b32_e32 v139, 2, v64
	v_cmp_lt_i32_e32 vcc, v205, v204
	s_waitcnt vmcnt(7)
	v_mov_b32_e32 v136, v190
	v_mov_b32_e32 v137, v191
	v_add_u32_e32 v190, s2, v222
	v_mad_i64_i32 v[190:191], s[0:1], v190, s93, v[198:199]
	global_load_dwordx2 v[190:191], v[190:191], off offset:32
	v_lshlrev_b32_e32 v157, 16, v136
	v_and_b32_e32 v155, 0xffff0000, v136
	v_lshlrev_b32_e32 v136, 16, v137
	v_and_b32_e32 v137, 0xffff0000, v137
	v_pk_fma_f32 v[136:137], v[136:137], s[30:31], v[116:117] op_sel_hi:[1,0,1]
	v_mov_b32_e32 v159, v157
	v_mul_f32_e32 v116, v136, v136
	v_pk_fma_f32 v[150:151], v[136:137], v[136:137], v[116:117] op_sel_hi:[1,1,0]
	v_mov_b32_e32 v153, v155
	v_mov_b32_e32 v150, v65
	v_cndmask_b32_e32 v64, v203, v205, vcc
	v_lshlrev_b32_e32 v64, 2, v64
	s_waitcnt vmcnt(6)
	v_mov_b32_e32 v116, v192
	v_mov_b32_e32 v117, v193
	v_mov_b32_e32 v140, v194
	v_mov_b32_e32 v141, v195
	v_add_u32_e32 v192, s2, v222
	v_mad_i64_i32 v[192:193], s[0:1], v192, s93, v[198:199]
	global_load_dwordx2 v[192:193], v[192:193], off offset:256
	v_add_u32_e32 v194, s2, v222
	v_mad_i64_i32 v[194:195], s[0:1], v194, s93, v[198:199]
	global_load_dwordx2 v[194:195], v[194:195], off offset:288
	v_lshlrev_b32_e32 v142, 16, v116
	v_and_b32_e32 v143, 0xffff0000, v116
	v_lshlrev_b32_e32 v116, 16, v117
	v_and_b32_e32 v117, 0xffff0000, v117
	v_pk_fma_f32 v[128:129], v[116:117], s[30:31], v[128:129] op_sel_hi:[1,0,1]
	v_lshlrev_b32_e32 v116, 16, v140
	v_and_b32_e32 v117, 0xffff0000, v140
	v_pk_fma_f32 v[116:117], v[116:117], s[30:31], v[122:123] op_sel_hi:[1,0,1]
	v_lshlrev_b32_e32 v122, 16, v141
	v_and_b32_e32 v123, 0xffff0000, v141
	v_pk_fma_f32 v[122:123], v[122:123], s[30:31], v[124:125] op_sel_hi:[1,0,1]
	v_mov_b32_e32 v124, v118
	v_mov_b32_e32 v125, v114
	v_pk_mov_b32 v[118:119], v[118:119], v[114:115] op_sel:[1,0]
	v_mov_b32_e32 v114, v120
	v_pk_fma_f32 v[124:125], v[156:157], s[30:31], v[124:125] op_sel_hi:[1,0,1]
	v_pk_fma_f32 v[140:141], v[158:159], s[30:31], v[118:119] op_sel_hi:[1,0,1]
	v_pk_fma_f32 v[118:119], v[154:155], s[30:31], v[114:115] op_sel_hi:[1,0,1]
	v_mov_b32_e32 v114, v121
	v_pk_fma_f32 v[120:121], v[152:153], s[30:31], v[114:115] op_sel_hi:[1,0,1]
	v_pk_mul_f32 v[114:115], v[124:125], v[124:125]
	v_pk_mul_f32 v[152:153], v[140:141], v[140:141]
	v_pk_mul_f32 v[154:155], v[118:119], v[118:119]
	v_pk_mul_f32 v[156:157], v[120:121], v[120:121]
	v_pk_mov_b32 v[114:115], v[124:125], v[114:115] op_sel:[1,0]
	v_pk_mov_b32 v[152:153], v[118:119], v[152:153] op_sel:[1,0]
	v_pk_fma_f32 v[126:127], v[142:143], s[30:31], v[126:127] op_sel_hi:[1,0,1]
	v_pk_add_f32 v[114:115], v[114:115], v[152:153]
	v_mov_b32_e32 v152, v136
	v_mov_b32_e32 v153, v154
	v_pk_mov_b32 v[154:155], v[136:137], v[156:157] op_sel:[1,0]
	v_pk_mul_f32 v[156:157], v[118:119], v[120:121]
	v_pk_add_f32 v[152:153], v[152:153], v[154:155]
	v_pk_mul_f32 v[154:155], v[124:125], v[140:141]
	v_pk_add_f32 v[114:115], v[114:115], v[152:153]
	v_pk_add_f32 v[152:153], v[124:125], v[140:141]
	v_pk_mul_f32 v[148:149], v[126:127], v[126:127]
	v_mov_b32_e32 v153, v155
	v_pk_add_f32 v[154:155], v[118:119], v[120:121]
	v_pk_mul_f32 v[144:145], v[128:129], v[128:129]
	v_mov_b32_e32 v155, v157
	v_pk_add_f32 v[152:153], v[152:153], v[154:155]
	v_pk_mul_f32 v[146:147], v[116:117], v[116:117]
	v_pk_add_f32 v[150:151], v[152:153], v[150:151]
	v_pk_mul_f32 v[142:143], v[122:123], v[122:123]
	v_pk_add_f32 v[114:115], v[114:115], v[150:151]
	v_mov_b32_e32 v150, v126
	v_mov_b32_e32 v151, v148
	v_mov_b32_e32 v148, v127
	v_pk_add_f32 v[148:149], v[150:151], v[148:149]
	v_mov_b32_e32 v150, v128
	v_mov_b32_e32 v151, v144
	v_mov_b32_e32 v144, v129
	v_pk_add_f32 v[144:145], v[150:151], v[144:145]
	s_nop 0
	v_pk_add_f32 v[144:145], v[148:149], v[144:145]
	s_nop 0
	v_pk_add_f32 v[114:115], v[114:115], v[144:145]
	v_mov_b32_e32 v144, v116
	v_mov_b32_e32 v145, v146
	v_mov_b32_e32 v146, v117
	v_pk_add_f32 v[144:145], v[144:145], v[146:147]
	v_mov_b32_e32 v146, v122
	v_mov_b32_e32 v147, v142
	v_mov_b32_e32 v142, v123
	v_pk_add_f32 v[142:143], v[146:147], v[142:143]
	s_nop 0
	v_pk_add_f32 v[142:143], v[144:145], v[142:143]
	s_nop 0
	v_pk_add_f32 v[114:115], v[114:115], v[142:143]
	v_mov_b32_e32 v142, v114
	v_mov_b32_e32 v143, v115
	s_nop 1
	v_permlane16_swap_b32_e32 v114, v142
	v_permlane16_swap_b32_e32 v115, v143
	v_pk_add_f32 v[114:115], v[114:115], v[142:143]
	v_mov_b32_e32 v142, v114
	v_mov_b32_e32 v143, v115
	s_nop 1
	v_permlane32_swap_b32_e32 v114, v142
	v_permlane32_swap_b32_e32 v115, v143
	s_and_saveexec_b64 s[0:1], s[40:41]
	s_cbranch_execz .LBB0_553
	s_waitcnt lgkmcnt(0)
	v_pk_add_f32 v[114:115], v[114:115], v[142:143]
	ds_write_b64 v230, v[114:115]
;     __device__ __forceinline__ void fused(f32x4 (&acc)[2][2][4][2], const Unit& u, int wr, int wc, int fr, int fq, LAS unsigned char* lds) const {
;     ...
;             for (int m = 0; m < 4; ++m) { const int rl = rl0 + ai * HALF + m * 16; const size_t roff = (size_t)(u.pm * BM + rl) * LDX + col0; float s = 0.f, q = 0.f;
; #pragma unroll
;                 for (int bj = 0; bj < 2; ++bj)
; #pragma unroll
;                     for (int n = 0; n < 2; ++n) { const u32x2 w = *(const u32x2*)(res + roff + bj * HALF + n * 16); f32x4 o = acc[ai][bj][m][n];
;                         o[0] += ALPHA * __uint_as_float(w.x << 16); o[1] += ALPHA * __uint_as_float(w.x & 0xffff0000u); o[2] += ALPHA * __uint_as_float(w.y << 16); o[3] += ALPHA * __uint_as_float(w.y & 0xffff0000u);
;                         acc[ai][bj][m][n] = o; s += (o[0] + o[1]) + (o[2] + o[3]); q += (o[0] * o[0] + o[1] * o[1]) + (o[2] * o[2] + o[3] * o[3]); }
;                 s += __shfl_xor(s, 16); s += __shfl_xor(s, 32); q += __shfl_xor(q, 16); q += __shfl_xor(q, 32);
;                 if (fq == 0) { P[(rl * 4 + wc) * 2] = s; P[(rl * 4 + wc) * 2 + 1] = q; }
.LBB0_553:
	s_or_b64 exec, exec, s[0:1]
	s_waitcnt lgkmcnt(1)
	v_add_u32_e32 v142, s2, v221
	v_mov_b64_e32 v[114:115], s[28:29]
	v_mad_i64_i32 v[114:115], s[0:1], v142, s93, v[114:115]
	v_lshl_add_u64 v[144:145], v[134:135], 1, v[114:115]
	s_waitcnt vmcnt(7)
	v_mov_b32_e32 v114, v196
	v_mov_b32_e32 v115, v197
	v_add_u32_e32 v196, s2, v223
	v_mad_i64_i32 v[196:197], s[0:1], v196, s93, v[198:199]
	global_load_dwordx2 v[196:197], v[196:197], off
	v_lshlrev_b32_e32 v160, 16, v114
	v_and_b32_e32 v162, 0xffff0000, v114
	v_lshlrev_b32_e32 v158, 16, v115
	v_and_b32_e32 v156, 0xffff0000, v115
	s_waitcnt vmcnt(7)
	v_mov_b32_e32 v114, v208
	v_mov_b32_e32 v115, v209
	v_add_u32_e32 v208, s2, v223
	v_mad_i64_i32 v[208:209], s[0:1], v208, s93, v[198:199]
	global_load_dwordx2 v[208:209], v[208:209], off offset:32
	v_lshlrev_b32_e32 v161, 16, v114
	v_and_b32_e32 v159, 0xffff0000, v114
	v_lshlrev_b32_e32 v114, 16, v115
	v_and_b32_e32 v115, 0xffff0000, v115
	v_pk_fma_f32 v[114:115], v[114:115], s[30:31], v[100:101] op_sel_hi:[1,0,1]
	v_mov_b32_e32 v163, v161
	v_mul_f32_e32 v100, v114, v114
	v_pk_fma_f32 v[154:155], v[114:115], v[114:115], v[100:101] op_sel_hi:[1,1,0]
	v_mov_b32_e32 v157, v159
	v_mov_b32_e32 v154, v65
	s_waitcnt vmcnt(7)
	v_mov_b32_e32 v100, v210
	v_mov_b32_e32 v101, v211
	v_add_u32_e32 v210, s2, v223
	v_mad_i64_i32 v[210:211], s[0:1], v210, s93, v[198:199]
	global_load_dwordx2 v[210:211], v[210:211], off offset:256
	v_lshlrev_b32_e32 v146, 16, v100
	v_and_b32_e32 v147, 0xffff0000, v100
	v_lshlrev_b32_e32 v100, 16, v101
	v_and_b32_e32 v101, 0xffff0000, v101
	v_pk_fma_f32 v[112:113], v[100:101], s[30:31], v[112:113] op_sel_hi:[1,0,1]
	s_waitcnt vmcnt(7)
	v_mov_b32_e32 v144, v212
	v_mov_b32_e32 v145, v213
	v_add_u32_e32 v212, s2, v223
	v_mad_i64_i32 v[212:213], s[0:1], v212, s93, v[198:199]
	global_load_dwordx2 v[212:213], v[212:213], off offset:288
	v_lshlrev_b32_e32 v100, 16, v144
	v_and_b32_e32 v101, 0xffff0000, v144
	v_pk_fma_f32 v[100:101], v[100:101], s[30:31], v[106:107] op_sel_hi:[1,0,1]
	v_lshlrev_b32_e32 v106, 16, v145
	v_and_b32_e32 v107, 0xffff0000, v145
	v_pk_fma_f32 v[106:107], v[106:107], s[30:31], v[108:109] op_sel_hi:[1,0,1]
	v_mov_b32_e32 v108, v102
	v_mov_b32_e32 v109, v98
	v_pk_mov_b32 v[102:103], v[102:103], v[98:99] op_sel:[1,0]
	v_mov_b32_e32 v98, v104
	v_pk_fma_f32 v[108:109], v[160:161], s[30:31], v[108:109] op_sel_hi:[1,0,1]
	v_pk_fma_f32 v[144:145], v[162:163], s[30:31], v[102:103] op_sel_hi:[1,0,1]
	v_pk_fma_f32 v[102:103], v[158:159], s[30:31], v[98:99] op_sel_hi:[1,0,1]
	v_mov_b32_e32 v98, v105
	v_pk_fma_f32 v[104:105], v[156:157], s[30:31], v[98:99] op_sel_hi:[1,0,1]
	v_pk_mul_f32 v[98:99], v[108:109], v[108:109]
	v_pk_mul_f32 v[156:157], v[144:145], v[144:145]
	v_pk_mul_f32 v[158:159], v[102:103], v[102:103]
	v_pk_mul_f32 v[160:161], v[104:105], v[104:105]
	v_pk_mov_b32 v[98:99], v[108:109], v[98:99] op_sel:[1,0]
	v_pk_mov_b32 v[156:157], v[102:103], v[156:157] op_sel:[1,0]
	v_pk_fma_f32 v[110:111], v[146:147], s[30:31], v[110:111] op_sel_hi:[1,0,1]
	v_pk_add_f32 v[98:99], v[98:99], v[156:157]
	v_mov_b32_e32 v156, v114
	v_mov_b32_e32 v157, v158
	v_pk_mov_b32 v[158:159], v[114:115], v[160:161] op_sel:[1,0]
	v_pk_mul_f32 v[160:161], v[102:103], v[104:105]
	v_pk_add_f32 v[156:157], v[156:157], v[158:159]
	v_pk_mul_f32 v[158:159], v[108:109], v[144:145]
	v_pk_add_f32 v[98:99], v[98:99], v[156:157]
	v_pk_add_f32 v[156:157], v[108:109], v[144:145]
	v_pk_mul_f32 v[152:153], v[110:111], v[110:111]
	v_mov_b32_e32 v157, v159
	v_pk_add_f32 v[158:159], v[102:103], v[104:105]
	v_pk_mul_f32 v[148:149], v[112:113], v[112:113]
	v_mov_b32_e32 v159, v161
	v_pk_add_f32 v[156:157], v[156:157], v[158:159]
	v_pk_mul_f32 v[150:151], v[100:101], v[100:101]
	v_pk_add_f32 v[154:155], v[156:157], v[154:155]
	v_pk_mul_f32 v[146:147], v[106:107], v[106:107]
	v_pk_add_f32 v[98:99], v[98:99], v[154:155]
	v_mov_b32_e32 v154, v110
	v_mov_b32_e32 v155, v152
	v_mov_b32_e32 v152, v111
	v_pk_add_f32 v[152:153], v[154:155], v[152:153]
	v_mov_b32_e32 v154, v112
	v_mov_b32_e32 v155, v148
	v_mov_b32_e32 v148, v113
	v_pk_add_f32 v[148:149], v[154:155], v[148:149]
	s_nop 0
	v_pk_add_f32 v[148:149], v[152:153], v[148:149]
	s_nop 0
	v_pk_add_f32 v[98:99], v[98:99], v[148:149]
	v_mov_b32_e32 v148, v100
	v_mov_b32_e32 v149, v150
	v_mov_b32_e32 v150, v101
	v_pk_add_f32 v[148:149], v[148:149], v[150:151]
	v_mov_b32_e32 v150, v106
	v_mov_b32_e32 v151, v146
	v_mov_b32_e32 v146, v107
	v_pk_add_f32 v[146:147], v[150:151], v[146:147]
	s_nop 0
	v_pk_add_f32 v[146:147], v[148:149], v[146:147]
	s_nop 0
	v_pk_add_f32 v[98:99], v[98:99], v[146:147]
	v_mov_b32_e32 v146, v98
	v_mov_b32_e32 v147, v99
	s_nop 1
	v_permlane16_swap_b32_e32 v98, v146
	v_permlane16_swap_b32_e32 v99, v147
	v_pk_add_f32 v[98:99], v[98:99], v[146:147]
	v_mov_b32_e32 v146, v98
	v_mov_b32_e32 v147, v99
	s_nop 1
	v_permlane32_swap_b32_e32 v98, v146
	v_permlane32_swap_b32_e32 v99, v147
	s_and_saveexec_b64 s[0:1], s[40:41]
	s_cbranch_execz .LBB0_555
	s_waitcnt lgkmcnt(0)
	v_pk_add_f32 v[98:99], v[98:99], v[146:147]
	ds_write_b64 v231, v[98:99]
;     __device__ __forceinline__ void fused(f32x4 (&acc)[2][2][4][2], const Unit& u, int wr, int wc, int fr, int fq, LAS unsigned char* lds) const {
;     ...
;             for (int m = 0; m < 4; ++m) { const int rl = rl0 + ai * HALF + m * 16; const size_t roff = (size_t)(u.pm * BM + rl) * LDX + col0; float s = 0.f, q = 0.f;
; #pragma unroll
;                 for (int bj = 0; bj < 2; ++bj)
; #pragma unroll
;                     for (int n = 0; n < 2; ++n) { const u32x2 w = *(const u32x2*)(res + roff + bj * HALF + n * 16); f32x4 o = acc[ai][bj][m][n];
;                         o[0] += ALPHA * __uint_as_float(w.x << 16); o[1] += ALPHA * __uint_as_float(w.x & 0xffff0000u); o[2] += ALPHA * __uint_as_float(w.y << 16); o[3] += ALPHA * __uint_as_float(w.y & 0xffff0000u);
;                         acc[ai][bj][m][n] = o; s += (o[0] + o[1]) + (o[2] + o[3]); q += (o[0] * o[0] + o[1] * o[1]) + (o[2] * o[2] + o[3] * o[3]); }
;                 s += __shfl_xor(s, 16); s += __shfl_xor(s, 32); q += __shfl_xor(q, 16); q += __shfl_xor(q, 32);
;                 if (fq == 0) { P[(rl * 4 + wc) * 2] = s; P[(rl * 4 + wc) * 2 + 1] = q; }
.LBB0_555:
	s_or_b64 exec, exec, s[0:1]
	s_waitcnt lgkmcnt(1)
	v_add_u32_e32 v146, s2, v222
	v_mov_b64_e32 v[98:99], s[28:29]
	v_mad_i64_i32 v[98:99], s[0:1], v146, s93, v[98:99]
	v_lshl_add_u64 v[148:149], v[134:135], 1, v[98:99]
	s_waitcnt vmcnt(7)
	v_mov_b32_e32 v98, v188
	v_mov_b32_e32 v99, v189
	v_add_u32_e32 v188, s2, v224
	v_mad_i64_i32 v[188:189], s[0:1], v188, s93, v[198:199]
	global_load_dwordx2 v[188:189], v[188:189], off
	v_lshlrev_b32_e32 v164, 16, v98
	v_and_b32_e32 v166, 0xffff0000, v98
	v_lshlrev_b32_e32 v162, 16, v99
	v_and_b32_e32 v160, 0xffff0000, v99
	s_waitcnt vmcnt(7)
	v_mov_b32_e32 v98, v190
	v_mov_b32_e32 v99, v191
	v_add_u32_e32 v190, s2, v224
	v_mad_i64_i32 v[190:191], s[0:1], v190, s93, v[198:199]
	global_load_dwordx2 v[190:191], v[190:191], off offset:32
	v_lshlrev_b32_e32 v165, 16, v98
	v_and_b32_e32 v163, 0xffff0000, v98
	v_lshlrev_b32_e32 v98, 16, v99
	v_and_b32_e32 v99, 0xffff0000, v99
	v_pk_fma_f32 v[98:99], v[98:99], s[30:31], v[84:85] op_sel_hi:[1,0,1]
	v_mov_b32_e32 v167, v165
	v_mul_f32_e32 v84, v98, v98
	v_pk_fma_f32 v[158:159], v[98:99], v[98:99], v[84:85] op_sel_hi:[1,1,0]
	v_mov_b32_e32 v161, v163
	v_mov_b32_e32 v158, v65
	s_waitcnt vmcnt(7)
	v_mov_b32_e32 v84, v192
	v_mov_b32_e32 v85, v193
	v_add_u32_e32 v192, s2, v224
	v_mad_i64_i32 v[192:193], s[0:1], v192, s93, v[198:199]
	global_load_dwordx2 v[192:193], v[192:193], off offset:256
	v_lshlrev_b32_e32 v150, 16, v84
	v_and_b32_e32 v151, 0xffff0000, v84
	v_lshlrev_b32_e32 v84, 16, v85
	v_and_b32_e32 v85, 0xffff0000, v85
	v_pk_fma_f32 v[96:97], v[84:85], s[30:31], v[96:97] op_sel_hi:[1,0,1]
	s_waitcnt vmcnt(7)
	v_mov_b32_e32 v148, v194
	v_mov_b32_e32 v149, v195
	v_add_u32_e32 v194, s2, v224
	v_mad_i64_i32 v[194:195], s[0:1], v194, s93, v[198:199]
	global_load_dwordx2 v[194:195], v[194:195], off offset:288
	v_lshlrev_b32_e32 v84, 16, v148
	v_and_b32_e32 v85, 0xffff0000, v148
	v_pk_fma_f32 v[84:85], v[84:85], s[30:31], v[90:91] op_sel_hi:[1,0,1]
	v_lshlrev_b32_e32 v90, 16, v149
	v_and_b32_e32 v91, 0xffff0000, v149
	v_pk_fma_f32 v[90:91], v[90:91], s[30:31], v[92:93] op_sel_hi:[1,0,1]
	v_mov_b32_e32 v92, v86
	v_mov_b32_e32 v93, v82
	v_pk_mov_b32 v[86:87], v[86:87], v[82:83] op_sel:[1,0]
	v_mov_b32_e32 v82, v88
	v_pk_fma_f32 v[92:93], v[164:165], s[30:31], v[92:93] op_sel_hi:[1,0,1]
	v_pk_fma_f32 v[148:149], v[166:167], s[30:31], v[86:87] op_sel_hi:[1,0,1]
	v_pk_fma_f32 v[86:87], v[162:163], s[30:31], v[82:83] op_sel_hi:[1,0,1]
	v_mov_b32_e32 v82, v89
	v_pk_fma_f32 v[88:89], v[160:161], s[30:31], v[82:83] op_sel_hi:[1,0,1]
	v_pk_mul_f32 v[82:83], v[92:93], v[92:93]
	v_pk_mul_f32 v[160:161], v[148:149], v[148:149]
	v_pk_mul_f32 v[162:163], v[86:87], v[86:87]
	v_pk_mul_f32 v[164:165], v[88:89], v[88:89]
	v_pk_mov_b32 v[82:83], v[92:93], v[82:83] op_sel:[1,0]
	v_pk_mov_b32 v[160:161], v[86:87], v[160:161] op_sel:[1,0]
	v_pk_fma_f32 v[94:95], v[150:151], s[30:31], v[94:95] op_sel_hi:[1,0,1]
	v_pk_add_f32 v[82:83], v[82:83], v[160:161]
	v_mov_b32_e32 v160, v98
	v_mov_b32_e32 v161, v162
	v_pk_mov_b32 v[162:163], v[98:99], v[164:165] op_sel:[1,0]
	v_pk_mul_f32 v[164:165], v[86:87], v[88:89]
	v_pk_add_f32 v[160:161], v[160:161], v[162:163]
	v_pk_mul_f32 v[162:163], v[92:93], v[148:149]
	v_pk_add_f32 v[82:83], v[82:83], v[160:161]
	v_pk_add_f32 v[160:161], v[92:93], v[148:149]
	v_pk_mul_f32 v[156:157], v[94:95], v[94:95]
	v_mov_b32_e32 v161, v163
	v_pk_add_f32 v[162:163], v[86:87], v[88:89]
	v_pk_mul_f32 v[152:153], v[96:97], v[96:97]
	v_mov_b32_e32 v163, v165
	v_pk_add_f32 v[160:161], v[160:161], v[162:163]
	v_pk_mul_f32 v[154:155], v[84:85], v[84:85]
	v_pk_add_f32 v[158:159], v[160:161], v[158:159]
	v_pk_mul_f32 v[150:151], v[90:91], v[90:91]
	v_pk_add_f32 v[82:83], v[82:83], v[158:159]
	v_mov_b32_e32 v158, v94
	v_mov_b32_e32 v159, v156
	v_mov_b32_e32 v156, v95
	v_pk_add_f32 v[156:157], v[158:159], v[156:157]
	v_mov_b32_e32 v158, v96
	v_mov_b32_e32 v159, v152
	v_mov_b32_e32 v152, v97
	v_pk_add_f32 v[152:153], v[158:159], v[152:153]
	s_nop 0
	v_pk_add_f32 v[152:153], v[156:157], v[152:153]
	s_nop 0
	v_pk_add_f32 v[82:83], v[82:83], v[152:153]
	v_mov_b32_e32 v152, v84
	v_mov_b32_e32 v153, v154
	v_mov_b32_e32 v154, v85
	v_pk_add_f32 v[152:153], v[152:153], v[154:155]
	v_mov_b32_e32 v154, v90
	v_mov_b32_e32 v155, v150
	v_mov_b32_e32 v150, v91
	v_pk_add_f32 v[150:151], v[154:155], v[150:151]
	s_nop 0
	v_pk_add_f32 v[150:151], v[152:153], v[150:151]
	s_nop 0
	v_pk_add_f32 v[82:83], v[82:83], v[150:151]
	v_mov_b32_e32 v150, v82
	v_mov_b32_e32 v151, v83
	s_nop 1
	v_permlane16_swap_b32_e32 v82, v150
	v_permlane16_swap_b32_e32 v83, v151
	v_pk_add_f32 v[82:83], v[82:83], v[150:151]
	v_mov_b32_e32 v150, v82
	v_mov_b32_e32 v151, v83
	s_nop 1
	v_permlane32_swap_b32_e32 v82, v150
	v_permlane32_swap_b32_e32 v83, v151
	s_and_saveexec_b64 s[0:1], s[40:41]
	s_cbranch_execz .LBB0_557
	s_waitcnt lgkmcnt(0)
	v_pk_add_f32 v[82:83], v[82:83], v[150:151]
	ds_write_b64 v232, v[82:83]
;     __device__ __forceinline__ void fused(f32x4 (&acc)[2][2][4][2], const Unit& u, int wr, int wc, int fr, int fq, LAS unsigned char* lds) const {
;     ...
;             for (int m = 0; m < 4; ++m) { const int rl = rl0 + ai * HALF + m * 16; const size_t roff = (size_t)(u.pm * BM + rl) * LDX + col0; float s = 0.f, q = 0.f;
; #pragma unroll
;                 for (int bj = 0; bj < 2; ++bj)
; #pragma unroll
;                     for (int n = 0; n < 2; ++n) { const u32x2 w = *(const u32x2*)(res + roff + bj * HALF + n * 16); f32x4 o = acc[ai][bj][m][n];
;                         o[0] += ALPHA * __uint_as_float(w.x << 16); o[1] += ALPHA * __uint_as_float(w.x & 0xffff0000u); o[2] += ALPHA * __uint_as_float(w.y << 16); o[3] += ALPHA * __uint_as_float(w.y & 0xffff0000u);
;                         acc[ai][bj][m][n] = o; s += (o[0] + o[1]) + (o[2] + o[3]); q += (o[0] * o[0] + o[1] * o[1]) + (o[2] * o[2] + o[3] * o[3]); }
;                 s += __shfl_xor(s, 16); s += __shfl_xor(s, 32); q += __shfl_xor(q, 16); q += __shfl_xor(q, 32);
;                 if (fq == 0) { P[(rl * 4 + wc) * 2] = s; P[(rl * 4 + wc) * 2 + 1] = q; }
.LBB0_557:
	s_or_b64 exec, exec, s[0:1]
	s_waitcnt lgkmcnt(1)
	v_add_u32_e32 v150, s2, v223
	v_mov_b64_e32 v[82:83], s[28:29]
	v_mad_i64_i32 v[82:83], s[0:1], v150, s93, v[82:83]
	v_lshl_add_u64 v[152:153], v[134:135], 1, v[82:83]
	s_waitcnt vmcnt(7)
	v_mov_b32_e32 v82, v196
	v_mov_b32_e32 v83, v197
	v_add_u32_e32 v196, s2, v225
	v_mad_i64_i32 v[196:197], s[0:1], v196, s93, v[198:199]
	global_load_dwordx2 v[196:197], v[196:197], off
	v_lshlrev_b32_e32 v168, 16, v82
	v_and_b32_e32 v170, 0xffff0000, v82
	v_lshlrev_b32_e32 v166, 16, v83
	v_and_b32_e32 v164, 0xffff0000, v83
	s_waitcnt vmcnt(7)
	v_mov_b32_e32 v82, v208
	v_mov_b32_e32 v83, v209
	v_add_u32_e32 v208, s2, v225
	v_mad_i64_i32 v[208:209], s[0:1], v208, s93, v[198:199]
	global_load_dwordx2 v[208:209], v[208:209], off offset:32
	v_lshlrev_b32_e32 v169, 16, v82
	v_and_b32_e32 v167, 0xffff0000, v82
	v_lshlrev_b32_e32 v82, 16, v83
	v_and_b32_e32 v83, 0xffff0000, v83
	v_pk_fma_f32 v[82:83], v[82:83], s[30:31], v[68:69] op_sel_hi:[1,0,1]
	v_mov_b32_e32 v171, v169
	v_mul_f32_e32 v68, v82, v82
	v_pk_fma_f32 v[162:163], v[82:83], v[82:83], v[68:69] op_sel_hi:[1,1,0]
	v_mov_b32_e32 v165, v167
	v_mov_b32_e32 v162, v65
	s_waitcnt vmcnt(7)
	v_mov_b32_e32 v68, v210
	v_mov_b32_e32 v69, v211
	v_add_u32_e32 v210, s2, v225
	v_mad_i64_i32 v[210:211], s[0:1], v210, s93, v[198:199]
	global_load_dwordx2 v[210:211], v[210:211], off offset:256
	v_lshlrev_b32_e32 v154, 16, v68
	v_and_b32_e32 v155, 0xffff0000, v68
	v_lshlrev_b32_e32 v68, 16, v69
	v_and_b32_e32 v69, 0xffff0000, v69
	v_pk_fma_f32 v[80:81], v[68:69], s[30:31], v[80:81] op_sel_hi:[1,0,1]
	s_waitcnt vmcnt(7)
	v_mov_b32_e32 v152, v212
	v_mov_b32_e32 v153, v213
	v_add_u32_e32 v212, s2, v225
	v_mad_i64_i32 v[212:213], s[0:1], v212, s93, v[198:199]
	global_load_dwordx2 v[212:213], v[212:213], off offset:288
	v_lshlrev_b32_e32 v68, 16, v152
	v_and_b32_e32 v69, 0xffff0000, v152
	v_pk_fma_f32 v[68:69], v[68:69], s[30:31], v[74:75] op_sel_hi:[1,0,1]
	v_lshlrev_b32_e32 v74, 16, v153
	v_and_b32_e32 v75, 0xffff0000, v153
	v_pk_fma_f32 v[74:75], v[74:75], s[30:31], v[76:77] op_sel_hi:[1,0,1]
	v_mov_b32_e32 v76, v70
	v_mov_b32_e32 v77, v66
	v_pk_mov_b32 v[70:71], v[70:71], v[66:67] op_sel:[1,0]
	v_mov_b32_e32 v66, v72
	v_pk_fma_f32 v[76:77], v[168:169], s[30:31], v[76:77] op_sel_hi:[1,0,1]
	v_pk_fma_f32 v[152:153], v[170:171], s[30:31], v[70:71] op_sel_hi:[1,0,1]
	v_pk_fma_f32 v[70:71], v[166:167], s[30:31], v[66:67] op_sel_hi:[1,0,1]
	v_mov_b32_e32 v66, v73
	v_pk_fma_f32 v[72:73], v[164:165], s[30:31], v[66:67] op_sel_hi:[1,0,1]
	v_pk_mul_f32 v[66:67], v[76:77], v[76:77]
	v_pk_mul_f32 v[164:165], v[152:153], v[152:153]
	v_pk_mul_f32 v[166:167], v[70:71], v[70:71]
	v_pk_mul_f32 v[168:169], v[72:73], v[72:73]
	v_pk_mov_b32 v[66:67], v[76:77], v[66:67] op_sel:[1,0]
	v_pk_mov_b32 v[164:165], v[70:71], v[164:165] op_sel:[1,0]
	v_pk_fma_f32 v[78:79], v[154:155], s[30:31], v[78:79] op_sel_hi:[1,0,1]
	v_pk_add_f32 v[66:67], v[66:67], v[164:165]
	v_mov_b32_e32 v164, v82
	v_mov_b32_e32 v165, v166
	v_pk_mov_b32 v[166:167], v[82:83], v[168:169] op_sel:[1,0]
	v_pk_mul_f32 v[168:169], v[70:71], v[72:73]
	v_pk_add_f32 v[164:165], v[164:165], v[166:167]
	v_pk_mul_f32 v[166:167], v[76:77], v[152:153]
	v_pk_add_f32 v[66:67], v[66:67], v[164:165]
	v_pk_add_f32 v[164:165], v[76:77], v[152:153]
	v_pk_mul_f32 v[160:161], v[78:79], v[78:79]
	v_mov_b32_e32 v165, v167
	v_pk_add_f32 v[166:167], v[70:71], v[72:73]
	v_pk_mul_f32 v[156:157], v[80:81], v[80:81]
	v_mov_b32_e32 v167, v169
	v_pk_add_f32 v[164:165], v[164:165], v[166:167]
	v_pk_mul_f32 v[158:159], v[68:69], v[68:69]
	v_pk_add_f32 v[162:163], v[164:165], v[162:163]
	v_pk_mul_f32 v[154:155], v[74:75], v[74:75]
	v_pk_add_f32 v[66:67], v[66:67], v[162:163]
	v_mov_b32_e32 v162, v78
	v_mov_b32_e32 v163, v160
	v_mov_b32_e32 v160, v79
	v_pk_add_f32 v[160:161], v[162:163], v[160:161]
	v_mov_b32_e32 v162, v80
	v_mov_b32_e32 v163, v156
	v_mov_b32_e32 v156, v81
	v_pk_add_f32 v[156:157], v[162:163], v[156:157]
	s_nop 0
	v_pk_add_f32 v[156:157], v[160:161], v[156:157]
	s_nop 0
	v_pk_add_f32 v[66:67], v[66:67], v[156:157]
	v_mov_b32_e32 v156, v68
	v_mov_b32_e32 v157, v158
	v_mov_b32_e32 v158, v69
	v_pk_add_f32 v[156:157], v[156:157], v[158:159]
	v_mov_b32_e32 v158, v74
	v_mov_b32_e32 v159, v154
	v_mov_b32_e32 v154, v75
	v_pk_add_f32 v[154:155], v[158:159], v[154:155]
	s_nop 0
	v_pk_add_f32 v[154:155], v[156:157], v[154:155]
	s_nop 0
	v_pk_add_f32 v[66:67], v[66:67], v[154:155]
	v_mov_b32_e32 v154, v66
	v_mov_b32_e32 v155, v67
	s_nop 1
	v_permlane16_swap_b32_e32 v66, v154
	v_permlane16_swap_b32_e32 v67, v155
	v_pk_add_f32 v[66:67], v[66:67], v[154:155]
	v_mov_b32_e32 v154, v66
	v_mov_b32_e32 v155, v67
	s_nop 1
	v_permlane32_swap_b32_e32 v66, v154
	v_permlane32_swap_b32_e32 v67, v155
	s_and_saveexec_b64 s[0:1], s[40:41]
	s_cbranch_execz .LBB0_559
	s_waitcnt lgkmcnt(0)
	v_pk_add_f32 v[66:67], v[66:67], v[154:155]
	ds_write_b64 v233, v[66:67]
;     __device__ __forceinline__ void fused(f32x4 (&acc)[2][2][4][2], const Unit& u, int wr, int wc, int fr, int fq, LAS unsigned char* lds) const {
;     ...
;             for (int m = 0; m < 4; ++m) { const int rl = rl0 + ai * HALF + m * 16; const size_t roff = (size_t)(u.pm * BM + rl) * LDX + col0; float s = 0.f, q = 0.f;
; #pragma unroll
;                 for (int bj = 0; bj < 2; ++bj)
; #pragma unroll
;                     for (int n = 0; n < 2; ++n) { const u32x2 w = *(const u32x2*)(res + roff + bj * HALF + n * 16); f32x4 o = acc[ai][bj][m][n];
;                         o[0] += ALPHA * __uint_as_float(w.x << 16); o[1] += ALPHA * __uint_as_float(w.x & 0xffff0000u); o[2] += ALPHA * __uint_as_float(w.y << 16); o[3] += ALPHA * __uint_as_float(w.y & 0xffff0000u);
;                         acc[ai][bj][m][n] = o; s += (o[0] + o[1]) + (o[2] + o[3]); q += (o[0] * o[0] + o[1] * o[1]) + (o[2] * o[2] + o[3] * o[3]); }
;                 s += __shfl_xor(s, 16); s += __shfl_xor(s, 32); q += __shfl_xor(q, 16); q += __shfl_xor(q, 32);
;                 if (fq == 0) { P[(rl * 4 + wc) * 2] = s; P[(rl * 4 + wc) * 2 + 1] = q; }
.LBB0_559:
	s_or_b64 exec, exec, s[0:1]
	s_waitcnt lgkmcnt(1)
	v_add_u32_e32 v154, s2, v224
	v_mov_b64_e32 v[66:67], s[28:29]
	v_mad_i64_i32 v[66:67], s[0:1], v154, s93, v[66:67]
	v_lshl_add_u64 v[156:157], v[134:135], 1, v[66:67]
	s_waitcnt vmcnt(7)
	v_mov_b32_e32 v66, v188
	v_mov_b32_e32 v67, v189
	v_add_u32_e32 v188, s2, v226
	v_mad_i64_i32 v[188:189], s[0:1], v188, s93, v[198:199]
	global_load_dwordx2 v[188:189], v[188:189], off
	v_lshlrev_b32_e32 v172, 16, v66
	v_and_b32_e32 v174, 0xffff0000, v66
	v_lshlrev_b32_e32 v170, 16, v67
	v_and_b32_e32 v168, 0xffff0000, v67
	s_waitcnt vmcnt(7)
	v_mov_b32_e32 v66, v190
	v_mov_b32_e32 v67, v191
	v_add_u32_e32 v190, s2, v226
	v_mad_i64_i32 v[190:191], s[0:1], v190, s93, v[198:199]
	global_load_dwordx2 v[190:191], v[190:191], off offset:32
	v_lshlrev_b32_e32 v173, 16, v66
	v_and_b32_e32 v171, 0xffff0000, v66
	v_lshlrev_b32_e32 v66, 16, v67
	v_and_b32_e32 v67, 0xffff0000, v67
	v_pk_fma_f32 v[66:67], v[66:67], s[30:31], v[50:51] op_sel_hi:[1,0,1]
	v_mov_b32_e32 v175, v173
	v_mul_f32_e32 v50, v66, v66
	v_pk_fma_f32 v[166:167], v[66:67], v[66:67], v[50:51] op_sel_hi:[1,1,0]
	v_mov_b32_e32 v169, v171
	v_mov_b32_e32 v166, v65
	s_waitcnt vmcnt(7)
	v_mov_b32_e32 v50, v192
	v_mov_b32_e32 v51, v193
	v_add_u32_e32 v192, s2, v226
	v_mad_i64_i32 v[192:193], s[0:1], v192, s93, v[198:199]
	global_load_dwordx2 v[192:193], v[192:193], off offset:256
	v_lshlrev_b32_e32 v158, 16, v50
	v_and_b32_e32 v159, 0xffff0000, v50
	v_lshlrev_b32_e32 v50, 16, v51
	v_and_b32_e32 v51, 0xffff0000, v51
	v_pk_fma_f32 v[62:63], v[50:51], s[30:31], v[62:63] op_sel_hi:[1,0,1]
	s_waitcnt vmcnt(7)
	v_mov_b32_e32 v156, v194
	v_mov_b32_e32 v157, v195
	v_add_u32_e32 v194, s2, v226
	v_mad_i64_i32 v[194:195], s[0:1], v194, s93, v[198:199]
	global_load_dwordx2 v[194:195], v[194:195], off offset:288
	v_lshlrev_b32_e32 v50, 16, v156
	v_and_b32_e32 v51, 0xffff0000, v156
	v_pk_fma_f32 v[50:51], v[50:51], s[30:31], v[56:57] op_sel_hi:[1,0,1]
	v_lshlrev_b32_e32 v56, 16, v157
	v_and_b32_e32 v57, 0xffff0000, v157
	v_pk_fma_f32 v[56:57], v[56:57], s[30:31], v[58:59] op_sel_hi:[1,0,1]
	v_mov_b32_e32 v58, v52
	v_mov_b32_e32 v59, v48
	v_pk_mov_b32 v[52:53], v[52:53], v[48:49] op_sel:[1,0]
	v_mov_b32_e32 v48, v54
	v_pk_fma_f32 v[58:59], v[172:173], s[30:31], v[58:59] op_sel_hi:[1,0,1]
	v_pk_fma_f32 v[156:157], v[174:175], s[30:31], v[52:53] op_sel_hi:[1,0,1]
	v_pk_fma_f32 v[52:53], v[170:171], s[30:31], v[48:49] op_sel_hi:[1,0,1]
	v_mov_b32_e32 v48, v55
	v_pk_fma_f32 v[54:55], v[168:169], s[30:31], v[48:49] op_sel_hi:[1,0,1]
	v_pk_mul_f32 v[48:49], v[58:59], v[58:59]
	v_pk_mul_f32 v[168:169], v[156:157], v[156:157]
	v_pk_mul_f32 v[170:171], v[52:53], v[52:53]
	v_pk_mul_f32 v[172:173], v[54:55], v[54:55]
	v_pk_mov_b32 v[48:49], v[58:59], v[48:49] op_sel:[1,0]
	v_pk_mov_b32 v[168:169], v[52:53], v[168:169] op_sel:[1,0]
	v_pk_fma_f32 v[60:61], v[158:159], s[30:31], v[60:61] op_sel_hi:[1,0,1]
	v_pk_add_f32 v[48:49], v[48:49], v[168:169]
	v_mov_b32_e32 v168, v66
	v_mov_b32_e32 v169, v170
	v_pk_mov_b32 v[170:171], v[66:67], v[172:173] op_sel:[1,0]
	v_pk_mul_f32 v[172:173], v[52:53], v[54:55]
	v_pk_add_f32 v[168:169], v[168:169], v[170:171]
	v_pk_mul_f32 v[170:171], v[58:59], v[156:157]
	v_pk_add_f32 v[48:49], v[48:49], v[168:169]
	v_pk_add_f32 v[168:169], v[58:59], v[156:157]
	v_pk_mul_f32 v[164:165], v[60:61], v[60:61]
	v_mov_b32_e32 v169, v171
	v_pk_add_f32 v[170:171], v[52:53], v[54:55]
	v_pk_mul_f32 v[160:161], v[62:63], v[62:63]
	v_mov_b32_e32 v171, v173
	v_pk_add_f32 v[168:169], v[168:169], v[170:171]
	v_pk_mul_f32 v[162:163], v[50:51], v[50:51]
	v_pk_add_f32 v[166:167], v[168:169], v[166:167]
	v_pk_mul_f32 v[158:159], v[56:57], v[56:57]
	v_pk_add_f32 v[48:49], v[48:49], v[166:167]
	v_mov_b32_e32 v166, v60
	v_mov_b32_e32 v167, v164
	v_mov_b32_e32 v164, v61
	v_pk_add_f32 v[164:165], v[166:167], v[164:165]
	v_mov_b32_e32 v166, v62
	v_mov_b32_e32 v167, v160
	v_mov_b32_e32 v160, v63
	v_pk_add_f32 v[160:161], v[166:167], v[160:161]
	s_nop 0
	v_pk_add_f32 v[160:161], v[164:165], v[160:161]
	s_nop 0
	v_pk_add_f32 v[48:49], v[48:49], v[160:161]
	v_mov_b32_e32 v160, v50
	v_mov_b32_e32 v161, v162
	v_mov_b32_e32 v162, v51
	v_pk_add_f32 v[160:161], v[160:161], v[162:163]
	v_mov_b32_e32 v162, v56
	v_mov_b32_e32 v163, v158
	v_mov_b32_e32 v158, v57
	v_pk_add_f32 v[158:159], v[162:163], v[158:159]
	s_nop 0
	v_pk_add_f32 v[158:159], v[160:161], v[158:159]
	s_nop 0
	v_pk_add_f32 v[48:49], v[48:49], v[158:159]
	v_mov_b32_e32 v158, v48
	v_mov_b32_e32 v159, v49
	s_nop 1
	v_permlane16_swap_b32_e32 v48, v158
	v_permlane16_swap_b32_e32 v49, v159
	v_pk_add_f32 v[48:49], v[48:49], v[158:159]
	v_mov_b32_e32 v158, v48
	v_mov_b32_e32 v159, v49
	s_nop 1
	v_permlane32_swap_b32_e32 v48, v158
	v_permlane32_swap_b32_e32 v49, v159
	s_and_saveexec_b64 s[0:1], s[40:41]
	s_cbranch_execz .LBB0_561
	s_waitcnt lgkmcnt(0)
	v_pk_add_f32 v[48:49], v[48:49], v[158:159]
	ds_write_b64 v234, v[48:49]
;     __device__ __forceinline__ void fused(f32x4 (&acc)[2][2][4][2], const Unit& u, int wr, int wc, int fr, int fq, LAS unsigned char* lds) const {
;     ...
;             for (int m = 0; m < 4; ++m) { const int rl = rl0 + ai * HALF + m * 16; const size_t roff = (size_t)(u.pm * BM + rl) * LDX + col0; float s = 0.f, q = 0.f;
; #pragma unroll
;                 for (int bj = 0; bj < 2; ++bj)
; #pragma unroll
;                     for (int n = 0; n < 2; ++n) { const u32x2 w = *(const u32x2*)(res + roff + bj * HALF + n * 16); f32x4 o = acc[ai][bj][m][n];
;                         o[0] += ALPHA * __uint_as_float(w.x << 16); o[1] += ALPHA * __uint_as_float(w.x & 0xffff0000u); o[2] += ALPHA * __uint_as_float(w.y << 16); o[3] += ALPHA * __uint_as_float(w.y & 0xffff0000u);
;                         acc[ai][bj][m][n] = o; s += (o[0] + o[1]) + (o[2] + o[3]); q += (o[0] * o[0] + o[1] * o[1]) + (o[2] * o[2] + o[3] * o[3]); }
;                 s += __shfl_xor(s, 16); s += __shfl_xor(s, 32); q += __shfl_xor(q, 16); q += __shfl_xor(q, 32);
;                 if (fq == 0) { P[(rl * 4 + wc) * 2] = s; P[(rl * 4 + wc) * 2 + 1] = q; }
.LBB0_561:
	s_or_b64 exec, exec, s[0:1]
	s_waitcnt lgkmcnt(1)
	v_add_u32_e32 v158, s2, v225
	v_mov_b64_e32 v[48:49], s[28:29]
	v_mad_i64_i32 v[48:49], s[0:1], v158, s93, v[48:49]
	v_lshl_add_u64 v[160:161], v[134:135], 1, v[48:49]
	s_waitcnt vmcnt(7)
	v_mov_b32_e32 v48, v196
	v_mov_b32_e32 v49, v197
	v_add_u32_e32 v196, s2, v227
	v_mad_i64_i32 v[196:197], s[0:1], v196, s93, v[198:199]
	global_load_dwordx2 v[196:197], v[196:197], off
	v_lshlrev_b32_e32 v176, 16, v48
	v_and_b32_e32 v178, 0xffff0000, v48
	v_lshlrev_b32_e32 v174, 16, v49
	v_and_b32_e32 v172, 0xffff0000, v49
	s_waitcnt vmcnt(7)
	v_mov_b32_e32 v48, v208
	v_mov_b32_e32 v49, v209
	v_add_u32_e32 v208, s2, v227
	v_mad_i64_i32 v[208:209], s[0:1], v208, s93, v[198:199]
	global_load_dwordx2 v[208:209], v[208:209], off offset:32
	v_lshlrev_b32_e32 v177, 16, v48
	v_and_b32_e32 v175, 0xffff0000, v48
	v_lshlrev_b32_e32 v48, 16, v49
	v_and_b32_e32 v49, 0xffff0000, v49
	v_pk_fma_f32 v[48:49], v[48:49], s[30:31], v[34:35] op_sel_hi:[1,0,1]
	v_mov_b32_e32 v179, v177
	v_mul_f32_e32 v34, v48, v48
	v_pk_fma_f32 v[170:171], v[48:49], v[48:49], v[34:35] op_sel_hi:[1,1,0]
	v_mov_b32_e32 v173, v175
	v_mov_b32_e32 v170, v65
	s_waitcnt vmcnt(7)
	v_mov_b32_e32 v34, v210
	v_mov_b32_e32 v35, v211
	v_add_u32_e32 v210, s2, v227
	v_mad_i64_i32 v[210:211], s[0:1], v210, s93, v[198:199]
	global_load_dwordx2 v[210:211], v[210:211], off offset:256
	v_lshlrev_b32_e32 v162, 16, v34
	v_and_b32_e32 v163, 0xffff0000, v34
	v_lshlrev_b32_e32 v34, 16, v35
	v_and_b32_e32 v35, 0xffff0000, v35
	v_pk_fma_f32 v[46:47], v[34:35], s[30:31], v[46:47] op_sel_hi:[1,0,1]
	s_waitcnt vmcnt(7)
	v_mov_b32_e32 v160, v212
	v_mov_b32_e32 v161, v213
	v_add_u32_e32 v212, s2, v227
	v_mad_i64_i32 v[212:213], s[0:1], v212, s93, v[198:199]
	global_load_dwordx2 v[212:213], v[212:213], off offset:288
	v_lshlrev_b32_e32 v34, 16, v160
	v_and_b32_e32 v35, 0xffff0000, v160
	v_pk_fma_f32 v[34:35], v[34:35], s[30:31], v[40:41] op_sel_hi:[1,0,1]
	v_lshlrev_b32_e32 v40, 16, v161
	v_and_b32_e32 v41, 0xffff0000, v161
	v_pk_fma_f32 v[40:41], v[40:41], s[30:31], v[42:43] op_sel_hi:[1,0,1]
	v_mov_b32_e32 v42, v36
	v_mov_b32_e32 v43, v32
	v_pk_mov_b32 v[36:37], v[36:37], v[32:33] op_sel:[1,0]
	v_mov_b32_e32 v32, v38
	v_pk_fma_f32 v[42:43], v[176:177], s[30:31], v[42:43] op_sel_hi:[1,0,1]
	v_pk_fma_f32 v[160:161], v[178:179], s[30:31], v[36:37] op_sel_hi:[1,0,1]
	v_pk_fma_f32 v[36:37], v[174:175], s[30:31], v[32:33] op_sel_hi:[1,0,1]
	v_mov_b32_e32 v32, v39
	v_pk_fma_f32 v[38:39], v[172:173], s[30:31], v[32:33] op_sel_hi:[1,0,1]
	v_pk_mul_f32 v[32:33], v[42:43], v[42:43]
	v_pk_mul_f32 v[172:173], v[160:161], v[160:161]
	v_pk_mul_f32 v[174:175], v[36:37], v[36:37]
	v_pk_mul_f32 v[176:177], v[38:39], v[38:39]
	v_pk_mov_b32 v[32:33], v[42:43], v[32:33] op_sel:[1,0]
	v_pk_mov_b32 v[172:173], v[36:37], v[172:173] op_sel:[1,0]
	v_pk_fma_f32 v[44:45], v[162:163], s[30:31], v[44:45] op_sel_hi:[1,0,1]
	v_pk_add_f32 v[32:33], v[32:33], v[172:173]
	v_mov_b32_e32 v172, v48
	v_mov_b32_e32 v173, v174
	v_pk_mov_b32 v[174:175], v[48:49], v[176:177] op_sel:[1,0]
	v_pk_mul_f32 v[176:177], v[36:37], v[38:39]
	v_pk_add_f32 v[172:173], v[172:173], v[174:175]
	v_pk_mul_f32 v[174:175], v[42:43], v[160:161]
	v_pk_add_f32 v[32:33], v[32:33], v[172:173]
	v_pk_add_f32 v[172:173], v[42:43], v[160:161]
	v_pk_mul_f32 v[168:169], v[44:45], v[44:45]
	v_mov_b32_e32 v173, v175
	v_pk_add_f32 v[174:175], v[36:37], v[38:39]
	v_pk_mul_f32 v[164:165], v[46:47], v[46:47]
	v_mov_b32_e32 v175, v177
	v_pk_add_f32 v[172:173], v[172:173], v[174:175]
	v_pk_mul_f32 v[166:167], v[34:35], v[34:35]
	v_pk_add_f32 v[170:171], v[172:173], v[170:171]
	v_pk_mul_f32 v[162:163], v[40:41], v[40:41]
	v_pk_add_f32 v[32:33], v[32:33], v[170:171]
	v_mov_b32_e32 v170, v44
	v_mov_b32_e32 v171, v168
	v_mov_b32_e32 v168, v45
	v_pk_add_f32 v[168:169], v[170:171], v[168:169]
	v_mov_b32_e32 v170, v46
	v_mov_b32_e32 v171, v164
	v_mov_b32_e32 v164, v47
	v_pk_add_f32 v[164:165], v[170:171], v[164:165]
	s_nop 0
	v_pk_add_f32 v[164:165], v[168:169], v[164:165]
	s_nop 0
	v_pk_add_f32 v[32:33], v[32:33], v[164:165]
	v_mov_b32_e32 v164, v34
	v_mov_b32_e32 v165, v166
	v_mov_b32_e32 v166, v35
	v_pk_add_f32 v[164:165], v[164:165], v[166:167]
	v_mov_b32_e32 v166, v40
	v_mov_b32_e32 v167, v162
	v_mov_b32_e32 v162, v41
	v_pk_add_f32 v[162:163], v[166:167], v[162:163]
	s_nop 0
	v_pk_add_f32 v[162:163], v[164:165], v[162:163]
	s_nop 0
	v_pk_add_f32 v[32:33], v[32:33], v[162:163]
	v_mov_b32_e32 v162, v32
	v_mov_b32_e32 v163, v33
	s_nop 1
	v_permlane16_swap_b32_e32 v32, v162
	v_permlane16_swap_b32_e32 v33, v163
	v_pk_add_f32 v[32:33], v[32:33], v[162:163]
	v_mov_b32_e32 v162, v32
	v_mov_b32_e32 v163, v33
	s_nop 1
	v_permlane32_swap_b32_e32 v32, v162
	v_permlane32_swap_b32_e32 v33, v163
	s_and_saveexec_b64 s[0:1], s[40:41]
	s_cbranch_execz .LBB0_563
	s_waitcnt lgkmcnt(0)
	v_pk_add_f32 v[32:33], v[32:33], v[162:163]
	ds_write_b64 v235, v[32:33]
;     __device__ __forceinline__ void fused(f32x4 (&acc)[2][2][4][2], const Unit& u, int wr, int wc, int fr, int fq, LAS unsigned char* lds) const {
;     ...
;             for (int m = 0; m < 4; ++m) { const int rl = rl0 + ai * HALF + m * 16; const size_t roff = (size_t)(u.pm * BM + rl) * LDX + col0; float s = 0.f, q = 0.f;
; #pragma unroll
;                 for (int bj = 0; bj < 2; ++bj)
; #pragma unroll
;                     for (int n = 0; n < 2; ++n) { const u32x2 w = *(const u32x2*)(res + roff + bj * HALF + n * 16); f32x4 o = acc[ai][bj][m][n];
;                         o[0] += ALPHA * __uint_as_float(w.x << 16); o[1] += ALPHA * __uint_as_float(w.x & 0xffff0000u); o[2] += ALPHA * __uint_as_float(w.y << 16); o[3] += ALPHA * __uint_as_float(w.y & 0xffff0000u);
;                         acc[ai][bj][m][n] = o; s += (o[0] + o[1]) + (o[2] + o[3]); q += (o[0] * o[0] + o[1] * o[1]) + (o[2] * o[2] + o[3] * o[3]); }
;                 s += __shfl_xor(s, 16); s += __shfl_xor(s, 32); q += __shfl_xor(q, 16); q += __shfl_xor(q, 32);
;                 if (fq == 0) { P[(rl * 4 + wc) * 2] = s; P[(rl * 4 + wc) * 2 + 1] = q; }
.LBB0_563:
	s_or_b64 exec, exec, s[0:1]
	v_add_u32_e32 v164, s2, v226
	v_mov_b64_e32 v[32:33], s[28:29]
	v_mad_i64_i32 v[32:33], s[0:1], v164, s93, v[32:33]
	v_lshl_add_u64 v[166:167], v[134:135], 1, v[32:33]
	s_waitcnt vmcnt(7)
	v_mov_b32_e32 v32, v188
	v_mov_b32_e32 v33, v189
	v_lshlrev_b32_e32 v180, 16, v32
	v_and_b32_e32 v182, 0xffff0000, v32
	s_waitcnt lgkmcnt(1)
	v_lshlrev_b32_e32 v162, 16, v33
	v_and_b32_e32 v168, 0xffff0000, v33
	s_waitcnt vmcnt(6)
	v_mov_b32_e32 v32, v190
	v_mov_b32_e32 v33, v191
	v_lshlrev_b32_e32 v181, 16, v32
	s_waitcnt lgkmcnt(0)
	v_and_b32_e32 v163, 0xffff0000, v32
	v_lshlrev_b32_e32 v32, 16, v33
	v_and_b32_e32 v33, 0xffff0000, v33
	v_pk_fma_f32 v[32:33], v[32:33], s[30:31], v[18:19] op_sel_hi:[1,0,1]
	v_mov_b32_e32 v183, v181
	v_mul_f32_e32 v18, v32, v32
	v_pk_fma_f32 v[178:179], v[32:33], v[32:33], v[18:19] op_sel_hi:[1,1,0]
	v_mov_b32_e32 v169, v163
	v_mov_b32_e32 v178, v65
	s_waitcnt vmcnt(5)
	v_mov_b32_e32 v18, v192
	v_mov_b32_e32 v19, v193
	v_lshlrev_b32_e32 v170, 16, v18
	v_and_b32_e32 v171, 0xffff0000, v18
	v_lshlrev_b32_e32 v18, 16, v19
	v_and_b32_e32 v19, 0xffff0000, v19
	v_pk_fma_f32 v[30:31], v[18:19], s[30:31], v[30:31] op_sel_hi:[1,0,1]
	s_waitcnt vmcnt(4)
	v_mov_b32_e32 v166, v194
	v_mov_b32_e32 v167, v195
	v_lshlrev_b32_e32 v18, 16, v166
	v_and_b32_e32 v19, 0xffff0000, v166
	v_pk_fma_f32 v[18:19], v[18:19], s[30:31], v[24:25] op_sel_hi:[1,0,1]
	v_lshlrev_b32_e32 v24, 16, v167
	v_and_b32_e32 v25, 0xffff0000, v167
	v_pk_fma_f32 v[24:25], v[24:25], s[30:31], v[26:27] op_sel_hi:[1,0,1]
	v_mov_b32_e32 v26, v20
	v_mov_b32_e32 v27, v16
	v_pk_mov_b32 v[20:21], v[20:21], v[16:17] op_sel:[1,0]
	v_mov_b32_e32 v16, v22
	v_pk_fma_f32 v[26:27], v[180:181], s[30:31], v[26:27] op_sel_hi:[1,0,1]
	v_pk_fma_f32 v[166:167], v[182:183], s[30:31], v[20:21] op_sel_hi:[1,0,1]
	v_pk_fma_f32 v[162:163], v[162:163], s[30:31], v[16:17] op_sel_hi:[1,0,1]
	v_mov_b32_e32 v16, v23
	v_pk_fma_f32 v[168:169], v[168:169], s[30:31], v[16:17] op_sel_hi:[1,0,1]
	v_pk_mul_f32 v[16:17], v[26:27], v[26:27]
	v_pk_mul_f32 v[20:21], v[166:167], v[166:167]
	v_pk_mul_f32 v[22:23], v[162:163], v[162:163]
	v_pk_mul_f32 v[180:181], v[168:169], v[168:169]
	v_pk_mov_b32 v[16:17], v[26:27], v[16:17] op_sel:[1,0]
	v_pk_mov_b32 v[20:21], v[162:163], v[20:21] op_sel:[1,0]
	v_pk_fma_f32 v[28:29], v[170:171], s[30:31], v[28:29] op_sel_hi:[1,0,1]
	v_pk_add_f32 v[16:17], v[16:17], v[20:21]
	v_mov_b32_e32 v20, v32
	v_mov_b32_e32 v21, v22
	v_pk_mov_b32 v[22:23], v[32:33], v[180:181] op_sel:[1,0]
	v_pk_mul_f32 v[180:181], v[162:163], v[168:169]
	v_pk_add_f32 v[20:21], v[20:21], v[22:23]
	v_pk_mul_f32 v[22:23], v[26:27], v[166:167]
	v_pk_add_f32 v[16:17], v[16:17], v[20:21]
	v_pk_add_f32 v[20:21], v[26:27], v[166:167]
	v_pk_mul_f32 v[176:177], v[28:29], v[28:29]
	v_mov_b32_e32 v21, v23
	v_pk_add_f32 v[22:23], v[162:163], v[168:169]
	v_pk_mul_f32 v[172:173], v[30:31], v[30:31]
	v_mov_b32_e32 v23, v181
	v_pk_add_f32 v[20:21], v[20:21], v[22:23]
	v_mov_b32_e32 v22, v30
	v_pk_add_f32 v[20:21], v[20:21], v[178:179]
	v_mov_b32_e32 v23, v172
	v_pk_add_f32 v[16:17], v[16:17], v[20:21]
	v_mov_b32_e32 v20, v28
	v_mov_b32_e32 v21, v176
	v_mov_b32_e32 v176, v29
	v_mov_b32_e32 v172, v31
	v_pk_add_f32 v[20:21], v[20:21], v[176:177]
	v_pk_add_f32 v[22:23], v[22:23], v[172:173]
	v_pk_mul_f32 v[174:175], v[18:19], v[18:19]
	v_pk_mul_f32 v[170:171], v[24:25], v[24:25]
	v_pk_add_f32 v[20:21], v[20:21], v[22:23]
	v_mov_b32_e32 v22, v24
	v_pk_add_f32 v[16:17], v[16:17], v[20:21]
	v_mov_b32_e32 v20, v18
	v_mov_b32_e32 v21, v174
	v_mov_b32_e32 v174, v19
	v_mov_b32_e32 v23, v170
	v_mov_b32_e32 v170, v25
	v_pk_add_f32 v[20:21], v[20:21], v[174:175]
	v_pk_add_f32 v[22:23], v[22:23], v[170:171]
	s_nop 0
	v_pk_add_f32 v[20:21], v[20:21], v[22:23]
	s_nop 0
	v_pk_add_f32 v[16:17], v[16:17], v[20:21]
	v_mov_b32_e32 v20, v16
	v_mov_b32_e32 v21, v17
	s_nop 1
	v_permlane16_swap_b32_e32 v16, v20
	v_permlane16_swap_b32_e32 v17, v21
	v_pk_add_f32 v[16:17], v[16:17], v[20:21]
	v_mov_b32_e32 v20, v16
	v_mov_b32_e32 v21, v17
	s_nop 1
	v_permlane32_swap_b32_e32 v16, v20
	v_permlane32_swap_b32_e32 v17, v21
	s_and_saveexec_b64 s[0:1], s[40:41]
	s_cbranch_execz .LBB0_565
	s_waitcnt lgkmcnt(0)
	v_pk_add_f32 v[16:17], v[16:17], v[20:21]
	ds_write_b64 v236, v[16:17]
;     __device__ __forceinline__ void fused(f32x4 (&acc)[2][2][4][2], const Unit& u, int wr, int wc, int fr, int fq, LAS unsigned char* lds) const {
;     ...
;             for (int m = 0; m < 4; ++m) { const int rl = rl0 + ai * HALF + m * 16; const size_t roff = (size_t)(u.pm * BM + rl) * LDX + col0; float s = 0.f, q = 0.f;
; #pragma unroll
;                 for (int bj = 0; bj < 2; ++bj)
; #pragma unroll
;                     for (int n = 0; n < 2; ++n) { const u32x2 w = *(const u32x2*)(res + roff + bj * HALF + n * 16); f32x4 o = acc[ai][bj][m][n];
;                         o[0] += ALPHA * __uint_as_float(w.x << 16); o[1] += ALPHA * __uint_as_float(w.x & 0xffff0000u); o[2] += ALPHA * __uint_as_float(w.y << 16); o[3] += ALPHA * __uint_as_float(w.y & 0xffff0000u);
;                         acc[ai][bj][m][n] = o; s += (o[0] + o[1]) + (o[2] + o[3]); q += (o[0] * o[0] + o[1] * o[1]) + (o[2] * o[2] + o[3] * o[3]); }
;                 s += __shfl_xor(s, 16); s += __shfl_xor(s, 32); q += __shfl_xor(q, 16); q += __shfl_xor(q, 32);
;                 if (fq == 0) { P[(rl * 4 + wc) * 2] = s; P[(rl * 4 + wc) * 2 + 1] = q; }
.LBB0_565:
	s_or_b64 exec, exec, s[0:1]
	v_add_u32_e32 v174, s2, v227
	v_mov_b64_e32 v[16:17], s[28:29]
	v_mad_i64_i32 v[16:17], s[0:1], v174, s93, v[16:17]
	v_lshl_add_u64 v[170:171], v[134:135], 1, v[16:17]
	s_waitcnt vmcnt(3)
	v_mov_b32_e32 v16, v196
	v_mov_b32_e32 v17, v197
	v_lshlrev_b32_e32 v180, 16, v16
	v_and_b32_e32 v186, 0xffff0000, v16
	v_lshlrev_b32_e32 v172, 16, v17
	v_and_b32_e32 v182, 0xffff0000, v17
	s_waitcnt vmcnt(2)
	v_mov_b32_e32 v16, v208
	v_mov_b32_e32 v17, v209
	v_lshlrev_b32_e32 v181, 16, v16
	v_and_b32_e32 v173, 0xffff0000, v16
	v_lshlrev_b32_e32 v16, 16, v17
	v_and_b32_e32 v17, 0xffff0000, v17
	v_pk_fma_f32 v[22:23], v[16:17], s[30:31], v[2:3] op_sel_hi:[1,0,1]
	v_mov_b32_e32 v187, v181
	v_mul_f32_e32 v2, v22, v22
	v_pk_fma_f32 v[184:185], v[22:23], v[22:23], v[2:3] op_sel_hi:[1,1,0]
	v_mov_b32_e32 v183, v173
	v_mov_b32_e32 v184, v65
	s_waitcnt vmcnt(1)
	v_mov_b32_e32 v2, v210
	v_mov_b32_e32 v3, v211
	v_lshlrev_b32_e32 v16, 16, v2
	v_and_b32_e32 v17, 0xffff0000, v2
	v_lshlrev_b32_e32 v2, 16, v3
	v_and_b32_e32 v3, 0xffff0000, v3
	s_waitcnt lgkmcnt(0)
	v_pk_fma_f32 v[20:21], v[2:3], s[30:31], v[14:15] op_sel_hi:[1,0,1]
	v_pk_fma_f32 v[16:17], v[16:17], s[30:31], v[12:13] op_sel_hi:[1,0,1]
	v_pk_mul_f32 v[176:177], v[20:21], v[20:21]
	v_pk_mul_f32 v[178:179], v[16:17], v[16:17]
	s_waitcnt vmcnt(0)
	v_mov_b32_e32 v2, v212
	v_mov_b32_e32 v3, v213
	v_lshlrev_b32_e32 v12, 16, v2
	v_and_b32_e32 v13, 0xffff0000, v2
	v_lshlrev_b32_e32 v2, 16, v3
	v_and_b32_e32 v3, 0xffff0000, v3
	v_pk_fma_f32 v[14:15], v[2:3], s[30:31], v[10:11] op_sel_hi:[1,0,1]
	v_mov_b32_e32 v10, v4
	v_mov_b32_e32 v11, v0
	v_pk_mov_b32 v[4:5], v[4:5], v[0:1] op_sel:[1,0]
	v_mov_b32_e32 v0, v6
	v_pk_fma_f32 v[170:171], v[180:181], s[30:31], v[10:11] op_sel_hi:[1,0,1]
	v_pk_fma_f32 v[180:181], v[186:187], s[30:31], v[4:5] op_sel_hi:[1,0,1]
	v_pk_fma_f32 v[172:173], v[172:173], s[30:31], v[0:1] op_sel_hi:[1,0,1]
	v_mov_b32_e32 v0, v7
	v_pk_fma_f32 v[182:183], v[182:183], s[30:31], v[0:1] op_sel_hi:[1,0,1]
	v_pk_mul_f32 v[0:1], v[170:171], v[170:171]
	v_pk_mul_f32 v[4:5], v[180:181], v[180:181]
	v_pk_mul_f32 v[6:7], v[172:173], v[172:173]
	v_pk_mul_f32 v[10:11], v[182:183], v[182:183]
	v_pk_mov_b32 v[0:1], v[170:171], v[0:1] op_sel:[1,0]
	v_pk_mov_b32 v[4:5], v[172:173], v[4:5] op_sel:[1,0]
	v_pk_fma_f32 v[12:13], v[12:13], s[30:31], v[8:9] op_sel_hi:[1,0,1]
	v_pk_add_f32 v[0:1], v[0:1], v[4:5]
	v_mov_b32_e32 v4, v22
	v_mov_b32_e32 v5, v6
	v_pk_mov_b32 v[6:7], v[22:23], v[10:11] op_sel:[1,0]
	v_pk_mul_f32 v[10:11], v[172:173], v[182:183]
	v_pk_add_f32 v[4:5], v[4:5], v[6:7]
	v_pk_mul_f32 v[6:7], v[170:171], v[180:181]
	v_pk_add_f32 v[0:1], v[0:1], v[4:5]
	v_pk_add_f32 v[4:5], v[170:171], v[180:181]
	v_pk_mul_f32 v[8:9], v[12:13], v[12:13]
	v_mov_b32_e32 v5, v7
	v_pk_add_f32 v[6:7], v[172:173], v[182:183]
	v_pk_mul_f32 v[2:3], v[14:15], v[14:15]
	v_mov_b32_e32 v7, v11
	v_pk_add_f32 v[4:5], v[4:5], v[6:7]
	v_mov_b32_e32 v6, v20
	v_pk_add_f32 v[4:5], v[4:5], v[184:185]
	v_mov_b32_e32 v7, v176
	v_pk_add_f32 v[0:1], v[0:1], v[4:5]
	v_mov_b32_e32 v4, v16
	v_mov_b32_e32 v5, v178
	v_mov_b32_e32 v178, v17
	v_mov_b32_e32 v176, v21
	v_pk_add_f32 v[4:5], v[4:5], v[178:179]
	v_pk_add_f32 v[6:7], v[6:7], v[176:177]
	s_nop 0
	v_pk_add_f32 v[4:5], v[4:5], v[6:7]
	v_mov_b32_e32 v6, v14
	v_pk_add_f32 v[0:1], v[0:1], v[4:5]
	v_mov_b32_e32 v4, v12
	v_mov_b32_e32 v5, v8
	v_mov_b32_e32 v8, v13
	v_mov_b32_e32 v7, v2
	v_mov_b32_e32 v2, v15
	v_pk_add_f32 v[4:5], v[4:5], v[8:9]
	v_pk_add_f32 v[2:3], v[6:7], v[2:3]
	s_nop 0
	v_pk_add_f32 v[2:3], v[4:5], v[2:3]
	s_nop 0
	v_pk_add_f32 v[0:1], v[0:1], v[2:3]
	v_mov_b32_e32 v2, v0
	v_mov_b32_e32 v3, v1
	s_nop 1
	v_permlane16_swap_b32_e32 v0, v2
	v_permlane16_swap_b32_e32 v1, v3
	v_pk_add_f32 v[0:1], v[0:1], v[2:3]
	v_mov_b32_e32 v2, v0
	v_mov_b32_e32 v3, v1
	s_nop 1
	v_permlane32_swap_b32_e32 v0, v2
	v_permlane32_swap_b32_e32 v1, v3
	s_and_saveexec_b64 s[0:1], s[40:41]
	s_cbranch_execz .LBB0_567
	s_waitcnt lgkmcnt(0)
	v_pk_add_f32 v[0:1], v[0:1], v[2:3]
	ds_write_b64 v237, v[0:1]
